# P5: odd-pm half of workgroups (cid bit3) start 5us late to serialize epilogue bursts
# speedup vs baseline: 1.0028x; 1.0028x over previous
.LBB0_870:
	v_readlane_b32 s0, v246, 4
	v_readlane_b32 s1, v246, 5
	s_cmp_lt_i32 s0, 6
	s_cselect_b64 s[0:1], -1, 0
	s_and_b64 s[2:3], s[0:1], s[2:3]
	s_andn2_b64 vcc, exec, s[2:3]
	s_cbranch_vccnz .LBB0_905
	s_bitcmp1_b32 s30, 3
	s_cbranch_scc0 .Lstg5_done
	s_sleep 127
	s_sleep 36
.Lstg5_done:
	s_add_u32 s2, s22, 0x119a4000
	s_addc_u32 s3, s23, 0
	s_add_u32 s6, s22, 0x580000
	s_addc_u32 s7, s23, 0
	s_movk_i32 s8, 0x80
	s_and_b64 s[4:5], s[68:69], exec
	s_cselect_b32 s33, s8, 0x84
	s_lshl_b32 s8, s33, 2
	s_cmp_lt_i32 s30, s8
	s_cselect_b64 s[4:5], -1, 0
	s_cmp_ge_i32 s30, s8
	v_readfirstlane_b32 s42, v202
	s_cbranch_scc1 .LBB0_873
	s_ashr_i32 s10, s30, 31
	s_lshr_b32 s10, s10, 29
	s_add_i32 s10, s30, s10
	s_ashr_i32 s11, s10, 3
	s_and_b32 s10, s10, -8
	s_sub_i32 s10, s30, s10
	s_lshr_b32 s9, s33, 1
	s_lshr_b32 s12, s10, 31
	s_or_b32 s9, s9, s12
	s_mul_i32 s9, s9, s10
	s_add_i32 s9, s9, s11
	s_ashr_i32 s10, s9, 31
	s_lshr_b32 s10, s10, 27
	s_add_i32 s10, s9, s10
	s_ashr_i32 s11, s10, 5
	s_lshl_b32 s12, s11, 3
	s_sub_i32 s11, s33, s12
	s_min_u32 s13, s11, 8
	s_andn2_b32 s10, s10, 31
	s_sub_i32 s9, s9, s10
	s_waitcnt lgkmcnt(0)
	v_cvt_f32_ubyte0_e32 v1, s13
	v_cvt_f32_i32_e32 v0, s9
	v_rcp_iflag_f32_e32 v2, v1
	s_ashr_i32 s10, s9, 30
	s_or_b32 s14, s10, 1
	v_mul_f32_e32 v2, v0, v2
	v_trunc_f32_e32 v2, v2
	v_fma_f32 v0, -v2, v1, v0
	v_cvt_i32_f32_e32 v2, v2
	v_cmp_ge_f32_e64 s[10:11], |v0|, v1
	s_and_b64 s[10:11], s[10:11], exec
	s_cselect_b32 s10, s14, 0
	v_readfirstlane_b32 s11, v2
	s_add_i32 s10, s11, s10
	s_mul_i32 s11, s10, s13
	s_sub_i32 s9, s9, s11
	s_sext_i32_i8 s9, s9
	s_add_i32 s24, s12, s9
	s_ashr_i32 s25, s24, 31
	s_lshl_b64 s[12:13], s[24:25], 19
	s_add_u32 s26, s2, s12
	s_sext_i32_i8 s65, s10
	s_addc_u32 s27, s3, s13
	s_bfe_i64 s[10:11], s[10:11], 0x80000
	s_lshl_b64 s[10:11], s[10:11], 19
	s_add_u32 s28, s6, s10
	s_addc_u32 s29, s7, s11
	s_andn2_b64 vcc, exec, s[4:5]
	s_cbranch_vccz .LBB0_874
	s_branch .LBB0_905
